# idle last-round workgroups of P3 / P9 convert the whole out-proj / down-proj weights (three register buffers, two tiles of prefetch); P0 / P1 no longer convert them
# speedup vs baseline: 1.0091x; 1.0045x over previous
; #define LAS __attribute__((address_space(3)))
; __device__ __forceinline__ TileDesc tile_desc(const Frame& F, int t) {
;     unsigned char* ws = F.ws; TileDesc d; int NT, idx; d.kind = 0;
;     if (t < 1536) { d.src = F.in[12]; d.ldn = NMOD; d.K = D; NT = 48; idx = t; d.dst = (bf16_t*)(ws + WS_WADA); }
;     else if (t < 2240) { d.src = F.in[14]; d.ldn = INW; d.K = D; NT = 22; idx = t - 1536; d.dst = (bf16_t*)(ws + WS_WIN); }
;     else if (t < 2496) { d.src = F.in[19]; d.ldn = D; d.K = D; NT = 8; idx = t - 2240; d.dst = (bf16_t*)(ws + WS_WOUT); }
;     else if (t < 3200) { d.src = F.in[20]; d.ldn = DFF; d.K = D; NT = 22; idx = t - 2496; d.dst = (bf16_t*)(ws + WS_WGU); d.kind = 1; }
;     else if (t < 3904) { d.src = F.in[21]; d.ldn = DFF; d.K = D; NT = 22; idx = t - 3200; d.dst = (bf16_t*)(ws + WS_WGU); d.kind = 2; }
;     else { d.src = F.in[22]; d.ldn = D; d.K = DFF; NT = 8; idx = t - 3904; d.dst = (bf16_t*)(ws + WS_WDN); }
;     d.n0 = (idx % NT) * 256; d.k0 = (idx / NT) * 64; return d;
; }
; __device__ __forceinline__ void convert_tiles(const Frame& F, int tlo, int thi, int wb, int nw) {
;     LAS float* tile = (LAS float*)F.lds;
;     int t = tlo + wb; if (t >= thi) return;
;     TileDesc d = tile_desc(F, t);
.LBB0_7:
	s_waitcnt lgkmcnt(0)
	v_writelane_b32 v245, s12, 21
	s_lshr_b32 s80, s8, 6
	s_cmp_lt_i32 s86, 1
	v_writelane_b32 v245, s13, 22
	v_writelane_b32 v245, s14, 23
	v_writelane_b32 v245, s15, 24
	v_writelane_b32 v245, s16, 25
	v_writelane_b32 v245, s17, 26
	v_writelane_b32 v245, s18, 27
	v_writelane_b32 v245, s19, 28
	v_writelane_b32 v245, s20, 29
	v_writelane_b32 v245, s21, 30
	v_writelane_b32 v245, s22, 31
	v_writelane_b32 v245, s23, 32
	v_writelane_b32 v245, s24, 33
	v_writelane_b32 v245, s25, 34
	v_writelane_b32 v245, s26, 35
	v_writelane_b32 v245, s27, 36
	s_load_dwordx16 s[12:27], s[0:1], 0x0
	s_cselect_b64 s[2:3], -1, 0
	s_cmp_gt_i32 s87, 0
	s_cselect_b64 s[4:5], -1, 0
	v_and_b32_e32 v160, 63, v144
	s_waitcnt lgkmcnt(0)
	v_writelane_b32 v245, s12, 37
	s_nop 1
	v_writelane_b32 v245, s13, 38
	v_writelane_b32 v245, s14, 39
	v_writelane_b32 v245, s15, 40
	v_writelane_b32 v245, s16, 41
	v_writelane_b32 v245, s17, 42
	v_writelane_b32 v245, s18, 43
	v_writelane_b32 v245, s19, 44
	v_writelane_b32 v245, s20, 45
	v_writelane_b32 v245, s21, 46
	v_writelane_b32 v245, s22, 47
	v_writelane_b32 v245, s23, 48
	v_writelane_b32 v245, s24, 49
	v_writelane_b32 v245, s25, 50
	v_writelane_b32 v245, s26, 51
	v_writelane_b32 v245, s27, 52
	s_and_b64 s[12:13], s[2:3], s[4:5]
	s_andn2_b64 vcc, exec, s[12:13]
	v_writelane_b32 v245, s8, 53
	s_cbranch_vccnz .LBB0_71
	s_cmpk_gt_i32 s33, 0x8bf
	s_cbranch_scc1 .LBB0_27
	s_cmpk_lt_i32 s33, 0x600
	s_mov_b32 s4, 48
	s_cbranch_scc1 .LBB0_13
	s_cmpk_gt_u32 s33, 0x8bf
	s_cbranch_scc0 .LBB0_14
	s_load_dwordx16 s[16:31], s[0:1], 0x80
	s_add_i32 s15, s33, 0xfffff740
	s_add_u32 s2, s84, 0x4600000
	s_addc_u32 s3, s85, 0
	s_waitcnt lgkmcnt(0)
	s_mov_b64 s[8:9], s[22:23]
	s_cbranch_execz .LBB0_15
	s_mov_b64 s[6:7], 0x800
	s_mov_b32 s4, 8
	s_branch .LBB0_16

; #define LAS __attribute__((address_space(3)))
; __device__ __forceinline__ void convert_tiles(const Frame& F, int tlo, int thi, int wb, int nw) {
;     ...
;     for (;;) {
; #pragma unroll
;         for (int i = 0; i < 8; ++i) { LAS float* tp = tile + (i * 8 + F.wave) * 257 + F.lane * 4; tp[0] = v[i][0]; tp[1] = v[i][1]; tp[2] = v[i][2]; tp[3] = v[i][3]; }
;         __syncthreads();
;         const int tn = t + nw; const bool more = tn < thi; TileDesc dn = d;
;         if (more) { dn = tile_desc(F, tn);
; #pragma unroll
;             for (int i = 0; i < 8; ++i) v[i] = __builtin_nontemporal_load((const f32x4*)(dn.src + (size_t)(dn.k0 + i * 8 + F.wave) * dn.ldn + dn.n0 + F.lane * 4)); }
.LBB0_20:
	s_add_i32 s5, s5, s88
	s_cmpk_gt_i32 s5, 0x8bf
	s_cselect_b64 s[18:19], -1, 0
	v_add_u32_e32 v37, 0xe0e8, v41
	s_and_b64 vcc, exec, s[18:19]
	s_mov_b32 s23, s14
	s_mov_b32 s20, s4
	s_waitcnt vmcnt(7)
	ds_write2_b32 v41, v2, v3 offset1:1
	ds_write2_b32 v41, v4, v5 offset0:2 offset1:3
	s_waitcnt vmcnt(6)
	ds_write2_b32 v42, v6, v7 offset1:1
	ds_write2_b32 v43, v8, v9 offset1:1
	s_waitcnt vmcnt(5)
	ds_write2_b32 v44, v10, v11 offset1:1
	ds_write2_b32 v45, v12, v13 offset1:1
	s_waitcnt vmcnt(4)
	ds_write2_b32 v46, v14, v15 offset1:1
	ds_write2_b32 v47, v16, v17 offset1:1
	s_waitcnt vmcnt(3)
	ds_write2_b32 v48, v18, v19 offset1:1
	ds_write2_b32 v49, v20, v21 offset1:1
	s_waitcnt vmcnt(2)
	ds_write2_b32 v53, v22, v23 offset1:1
	ds_write2_b32 v54, v24, v25 offset1:1
	s_waitcnt vmcnt(1)
	ds_write2_b32 v55, v26, v27 offset1:1
	ds_write2_b32 v56, v28, v29 offset1:1
	s_waitcnt vmcnt(0)
	ds_write2_b32 v57, v30, v31 offset1:1
	ds_write2_b32 v37, v32, v33 offset1:1
	s_waitcnt lgkmcnt(0)
	s_barrier
	s_cbranch_vccnz .LBB0_19
	s_cmpk_lt_i32 s5, 0x600
	s_cbranch_scc1 .LBB0_17
	s_cmpk_gt_u32 s5, 0x8bf
	s_cbranch_scc0 .LBB0_25
	s_load_dwordx16 s[36:51], s[0:1], 0x80
	s_add_i32 s15, s5, 0xfffff740
	s_waitcnt lgkmcnt(0)
	s_mov_b64 s[24:25], s[42:43]
	s_cbranch_execz .LBB0_26
	s_mov_b64 s[22:23], 0x800
	s_mov_b32 s20, 8
	s_mov_b64 s[16:17], s[6:7]
	s_branch .LBB0_18

; #define LAS __attribute__((address_space(3)))
; __device__ __forceinline__ void convert_tiles(const Frame& F, int tlo, int thi, int wb, int nw) {
;     LAS float* tile = (LAS float*)F.lds;
;     int t = tlo + wb; if (t >= thi) return;
;     TileDesc d = tile_desc(F, t);
; __global__ void __launch_bounds__(512, 2) fwd_mega(Params prm) {
;     ...
;     if (IN(1)) { { const int cb = F.G > 96 ? 48 : 0;
;           if (F.bid >= cb) convert_tiles(F, 2496, 4608, F.bid - cb, F.G - cb); }
.LBB0_83:
	s_cmp_lt_i32 s86, 2
	s_cselect_b64 s[4:5], -1, 0
	s_add_u32 s6, s84, 0x9100000
	s_addc_u32 s7, s85, 0
	s_and_b64 s[14:15], s[4:5], s[2:3]
	v_writelane_b32 v245, s6, 54
	s_andn2_b64 vcc, exec, s[14:15]
	s_nop 0
	v_writelane_b32 v245, s7, 55
	s_cbranch_vccnz .LBB0_143
	s_cmpk_gt_i32 s88, 0x60
	s_waitcnt lgkmcnt(0)
	s_cselect_b32 s16, 48, 0
	s_cmp_lt_i32 s33, s16
	s_cbranch_scc1 .LBB0_115
	s_sub_i32 s8, s33, s16
	s_cmpk_gt_u32 s8, 0x57f
	s_cbranch_scc1 .LBB0_115
	s_cmpk_lt_u32 s8, 0x2c0
	s_mov_b32 s13, 1
	s_cbranch_scc1 .LBB0_90
	s_cmpk_gt_u32 s8, 0x57f
	s_cbranch_scc0 .LBB0_91
	s_load_dwordx16 s[36:51], s[0:1], 0x80
	s_add_i32 s9, s8, 0xfffffa80
	s_waitcnt lgkmcnt(0)
	s_mov_b64 s[4:5], s[48:49]
	s_cbranch_execz .LBB0_92
	s_mov_b64 s[6:7], 0x7a00000
	s_mov_b64 s[2:3], 0x800
	s_movk_i32 s24, 0x1600
	s_mov_b32 s13, 0
	s_mov_b32 s12, 8
	s_branch .LBB0_93

; #define LAS __attribute__((address_space(3)))
; __device__ __forceinline__ void convert_tiles(const Frame& F, int tlo, int thi, int wb, int nw) {
;     ...
;     for (;;) {
; #pragma unroll
;         for (int i = 0; i < 8; ++i) { LAS float* tp = tile + (i * 8 + F.wave) * 257 + F.lane * 4; tp[0] = v[i][0]; tp[1] = v[i][1]; tp[2] = v[i][2]; tp[3] = v[i][3]; }
;         __syncthreads();
;         const int tn = t + nw; const bool more = tn < thi; TileDesc dn = d;
;         if (more) { dn = tile_desc(F, tn);
; #pragma unroll
;             for (int i = 0; i < 8; ++i) v[i] = __builtin_nontemporal_load((const f32x4*)(dn.src + (size_t)(dn.k0 + i * 8 + F.wave) * dn.ldn + dn.n0 + F.lane * 4)); }
; #pragma unroll
;         for (int it = 0; it < 4; ++it) { const int item = it * 512 + F.tid, n = item >> 3, kg = item & 7;
;             float f[8];
; #pragma unroll
;             for (int j = 0; j < 8; ++j) f[j] = tile[(kg * 8 + j) * 257 + n];
;             const int nn = d.n0 + n; const int row = d.kind == 0 ? nn : (((nn >> 7) << 8) + (nn & 127) + (d.kind == 2 ? 128 : 0));
;             *(u32x4*)(d.dst + (size_t)row * d.K + d.k0 + kg * 8) = pack8(f); }
;         __syncthreads();
;         if (!more) break;
;         t = tn; d = dn;
;     }
.LBB0_96:
	s_cmp_eq_u32 s13, 0
	v_add_u32_e32 v35, s27, v36
	ds_read_b32 v52, v45 offset:1028
	ds_read_b32 v53, v45 offset:3084
	ds_read_b32 v54, v45 offset:5140
	ds_read_b32 v55, v45 offset:7196
	ds_read_b32 v56, v45 offset:6168
	ds_read_b32 v57, v45 offset:4112
	ds_read_b32 v58, v45 offset:2056
	ds_read_b32 v59, v45
	s_cselect_b64 vcc, -1, 0
	s_cmp_eq_u32 s13, 2
	v_lshlrev_b32_e32 v60, 1, v35
	s_cselect_b32 s19, 0x80, 0
	s_ashr_i32 s13, s12, 31
	v_and_b32_e32 v60, 0xffffff00, v60
	s_lshl_b64 s[12:13], s[12:13], 1
	v_or3_b32 v60, v36, v60, s19
	s_add_u32 s10, s10, s12
	v_cndmask_b32_e32 v35, v60, v35, vcc
	s_addc_u32 s11, s11, s13
	s_waitcnt lgkmcnt(0)
	v_cvt_pk_bf16_f32 v52, v59, v52
	v_cvt_pk_bf16_f32 v53, v58, v53
	v_cvt_pk_bf16_f32 v54, v57, v54
	v_cvt_pk_bf16_f32 v55, v56, v55
	v_mad_u64_u32 v[56:57], s[12:13], v35, s24, 0
	v_ashrrev_i32_e32 v59, 31, v35
	v_mov_b32_e32 v58, v57
	v_mad_u64_u32 v[58:59], s[12:13], v59, s24, v[58:59]
	v_mov_b32_e32 v57, v58
	v_lshl_add_u64 v[56:57], v[56:57], 1, s[10:11]
	v_mov_b32_e32 v35, v33
	v_lshl_add_u64 v[56:57], v[56:57], 0, v[34:35]
	global_store_dwordx4 v[56:57], v[52:55], off
	ds_read_b32 v53, v46 offset:1028
	ds_read_b32 v54, v46 offset:3084
	ds_read_b32 v55, v46 offset:5140
	ds_read_b32 v56, v46 offset:7196
	ds_read_b32 v57, v46 offset:6168
	ds_read_b32 v58, v46 offset:4112
	ds_read_b32 v59, v46 offset:2056
	ds_read_b32 v60, v46
	v_add_u32_e32 v52, s27, v37
	v_lshlrev_b32_e32 v61, 1, v52
	v_and_b32_e32 v61, 0xffffff00, v61
	v_or3_b32 v61, v38, v61, s19
	v_cndmask_b32_e32 v61, v61, v52, vcc
	s_waitcnt lgkmcnt(0)
	v_cvt_pk_bf16_f32 v52, v60, v53
	v_cvt_pk_bf16_f32 v53, v59, v54
	v_cvt_pk_bf16_f32 v54, v58, v55
	v_cvt_pk_bf16_f32 v55, v57, v56
	v_mad_u64_u32 v[56:57], s[12:13], v61, s24, 0
	v_ashrrev_i32_e32 v59, 31, v61
	v_mov_b32_e32 v58, v57
	v_mad_u64_u32 v[58:59], s[12:13], v59, s24, v[58:59]
	v_mov_b32_e32 v57, v58
	v_lshl_add_u64 v[56:57], v[56:57], 1, s[10:11]
	v_lshl_add_u64 v[56:57], v[56:57], 0, v[34:35]
	global_store_dwordx4 v[56:57], v[52:55], off
	ds_read_b32 v53, v45 offset:1540
	ds_read_b32 v54, v45 offset:3596
	ds_read_b32 v55, v45 offset:5652
	ds_read_b32 v56, v45 offset:7708
	ds_read_b32 v57, v45 offset:6680
	ds_read_b32 v58, v45 offset:4624
	ds_read_b32 v59, v45 offset:2568
	ds_read_b32 v60, v45 offset:512
	v_add_u32_e32 v52, s27, v39
	v_lshlrev_b32_e32 v61, 1, v52
	v_and_b32_e32 v61, 0xffffff00, v61
	v_or3_b32 v61, v36, v61, s19
	v_cndmask_b32_e32 v61, v61, v52, vcc
	s_waitcnt lgkmcnt(0)
	v_cvt_pk_bf16_f32 v52, v60, v53
	v_cvt_pk_bf16_f32 v53, v59, v54
	v_cvt_pk_bf16_f32 v54, v58, v55
	v_cvt_pk_bf16_f32 v55, v57, v56
	v_mad_u64_u32 v[56:57], s[12:13], v61, s24, 0
	v_ashrrev_i32_e32 v59, 31, v61
	v_mov_b32_e32 v58, v57
	v_mad_u64_u32 v[58:59], s[12:13], v59, s24, v[58:59]
	v_mov_b32_e32 v57, v58
	v_lshl_add_u64 v[56:57], v[56:57], 1, s[10:11]
	v_lshl_add_u64 v[56:57], v[56:57], 0, v[34:35]
	global_store_dwordx4 v[56:57], v[52:55], off
	ds_read_b32 v53, v47 offset:1028
	ds_read_b32 v54, v47 offset:3084
	ds_read_b32 v55, v47 offset:5140
	ds_read_b32 v56, v47 offset:7196
	ds_read_b32 v57, v47 offset:6168
	ds_read_b32 v58, v47 offset:4112
	ds_read_b32 v59, v47 offset:2056
	ds_read_b32 v60, v47
	v_add_u32_e32 v52, s27, v40
	v_lshlrev_b32_e32 v61, 1, v52
	v_and_b32_e32 v61, 0xffffff00, v61
	v_or3_b32 v61, v41, v61, s19
	v_cndmask_b32_e32 v61, v61, v52, vcc
	s_waitcnt lgkmcnt(0)
	v_cvt_pk_bf16_f32 v52, v60, v53
	v_cvt_pk_bf16_f32 v53, v59, v54
	v_cvt_pk_bf16_f32 v54, v58, v55
	v_cvt_pk_bf16_f32 v55, v57, v56
	v_mad_u64_u32 v[56:57], s[12:13], v61, s24, 0
	v_ashrrev_i32_e32 v59, 31, v61
	v_mov_b32_e32 v58, v57
	v_mad_u64_u32 v[58:59], s[12:13], v59, s24, v[58:59]
	v_mov_b32_e32 v57, v58
	s_add_i32 s30, s30, s25
	v_lshl_add_u64 v[56:57], v[56:57], 1, s[10:11]
	s_add_i32 s10, s29, s30
	v_lshl_add_u64 v[56:57], v[56:57], 0, v[34:35]
	s_cmpk_lt_i32 s10, 0xf40
	s_mov_b64 s[10:11], s[16:17]
	s_mov_b32 s24, s31
	s_mov_b32 s12, s35
	s_mov_b32 s27, s18
	s_mov_b32 s13, s34
	global_store_dwordx4 v[56:57], v[52:55], off
	s_barrier
	s_cbranch_scc0 .LBB0_115
.LBB0_97:
	v_add_u32_e32 v35, 0x8080, v42
	s_waitcnt vmcnt(7)
	ds_write2_b32 v42, v0, v1 offset1:1
	ds_write2_b32 v42, v2, v3 offset0:2 offset1:3
	s_waitcnt vmcnt(6)
	ds_write2_b32 v43, v4, v5 offset1:1
	ds_write2_b32 v44, v6, v7 offset1:1
	s_waitcnt vmcnt(5)
	ds_write2_b32 v48, v8, v9 offset1:1
	ds_write2_b32 v49, v10, v11 offset1:1
	s_waitcnt vmcnt(4)
	ds_write2_b32 v50, v12, v13 offset1:1
	ds_write2_b32 v51, v14, v15 offset1:1
	s_waitcnt vmcnt(3)
	ds_write2_b32 v35, v16, v17 offset1:1
	v_add_u32_e32 v35, 0x8088, v42
	ds_write2_b32 v35, v18, v19 offset1:1
	v_add_u32_e32 v35, 0xa0a0, v42
	s_waitcnt vmcnt(2)
	ds_write2_b32 v35, v20, v21 offset1:1
	v_add_u32_e32 v35, 0xa0a8, v42
	ds_write2_b32 v35, v22, v23 offset1:1
	v_add_u32_e32 v35, 0xc0c0, v42
	s_waitcnt vmcnt(1)
	ds_write2_b32 v35, v24, v25 offset1:1
	v_add_u32_e32 v35, 0xc0c8, v42
	s_add_i32 s19, s28, s30
	ds_write2_b32 v35, v26, v27 offset1:1
	v_add_u32_e32 v35, 0xe0e0, v42
	s_add_i32 s26, s26, s25
	s_add_i32 s20, s19, 0x9c0
	s_waitcnt vmcnt(0)
	ds_write2_b32 v35, v28, v29 offset1:1
	v_add_u32_e32 v35, 0xe0e8, v42
	s_cmpk_gt_i32 s20, 0xf3f
	s_mov_b32 s35, s12
	s_mov_b32 s18, s27
	ds_write2_b32 v35, v30, v31 offset1:1
	s_waitcnt lgkmcnt(0)
	s_barrier
	s_cbranch_scc1 .LBB0_96
	s_cmpk_lt_i32 s20, 0x600
	s_cbranch_scc1 .LBB0_94
	s_cmpk_gt_u32 s20, 0x8bf
	s_cbranch_scc0 .LBB0_105
	s_cmpk_gt_u32 s20, 0x9bf
	s_cbranch_scc0 .LBB0_106
	s_cmpk_gt_u32 s20, 0xc7f
	s_cbranch_scc0 .LBB0_107
	s_cmpk_gt_u32 s20, 0xf3f
	s_cbranch_scc0 .LBB0_113
	s_load_dwordx16 s[36:51], s[0:1], 0x80
	s_add_i32 s52, s19, 0xfffffa80
	s_waitcnt lgkmcnt(0)
	s_mov_b64 s[22:23], s[48:49]
	s_cbranch_execz .LBB0_114
	s_mov_b64 s[20:21], 0x800
	s_movk_i32 s31, 0x1600
	s_mov_b32 s34, 0
	s_mov_b32 s35, 8
	s_mov_b64 s[16:17], s[2:3]
	s_cbranch_execz .LBB0_108
	s_branch .LBB0_109

; #define LAS __attribute__((address_space(3)))
; __device__ __forceinline__ void convert_tiles(const Frame& F, int tlo, int thi, int wb, int nw) {
;     LAS float* tile = (LAS float*)F.lds;
;     int t = tlo + wb; if (t >= thi) return;
;     TileDesc d = tile_desc(F, t);
;     f32x4 v[8];
; #pragma unroll
;     for (int i = 0; i < 8; ++i) v[i] = __builtin_nontemporal_load((const f32x4*)(d.src + (size_t)(d.k0 + i * 8 + F.wave) * d.ldn + d.n0 + F.lane * 4));
;     for (;;) {
; #pragma unroll
;         for (int i = 0; i < 8; ++i) { LAS float* tp = tile + (i * 8 + F.wave) * 257 + F.lane * 4; tp[0] = v[i][0]; tp[1] = v[i][1]; tp[2] = v[i][2]; tp[3] = v[i][3]; }
;         __syncthreads();
;         const int tn = t + nw; const bool more = tn < thi; TileDesc dn = d;
;         if (more) { dn = tile_desc(F, tn);
; #pragma unroll
;             for (int i = 0; i < 8; ++i) v[i] = __builtin_nontemporal_load((const f32x4*)(dn.src + (size_t)(dn.k0 + i * 8 + F.wave) * dn.ldn + dn.n0 + F.lane * 4)); }
.LBB0_295:
	s_waitcnt vmcnt(0)
	s_barrier
	s_cmpk_lt_i32 s33, 236
	s_cbranch_scc1 .Lmy_cv3_end
	s_sub_i32 s12, s33, 236
	s_cmpk_ge_i32 s12, 16
	s_cbranch_scc1 .Lmy_cv3_end
	s_add_i32 s12, s12, 0
	s_load_dwordx2 s[4:5], s[98:99], 0x98
	s_add_u32 s6, s84, 0x4600000
	s_addc_u32 s7, s85, 0
	v_lshlrev_b32_e32 v32, 4, v160
	s_mul_i32 s16, s80, 0x404
	v_add_u32_e32 v33, s16, v32
	v_and_b32_e32 v36, 7, v144
	v_lshrrev_b32_e32 v35, 3, v144
	v_mul_u32_u24_e32 v34, 0x2020, v36
	v_lshl_add_u32 v34, v35, 2, v34
	v_mov_b32_e32 v37, 0x1000
	v_mul_u32_u24_e32 v35, v35, v37
	v_lshl_add_u32 v35, v36, 4, v35
	s_waitcnt lgkmcnt(0)
	s_lshr_b32 s16, s12, 3
	s_and_b32 s17, s12, 7
	s_lshl_b32 s18, s16, 19
	s_lshl_b32 s19, s80, 13
	s_add_i32 s18, s18, s19
	s_lshl_b32 s19, s17, 10
	s_add_i32 s18, s18, s19
	s_add_u32 s8, s4, s18
	s_addc_u32 s9, s5, 0
	s_mul_i32 s18, s17, 0x100000
	s_lshl_b32 s19, s16, 7
	s_add_i32 s18, s18, s19
	s_mov_b32 s20, s18
	global_load_dwordx4 v[0:3], v32, s[8:9] nt
	s_add_u32 s8, s8, 0x10000
	s_addc_u32 s9, s9, 0
	global_load_dwordx4 v[4:7], v32, s[8:9] nt
	s_add_u32 s8, s8, 0x10000
	s_addc_u32 s9, s9, 0
	global_load_dwordx4 v[8:11], v32, s[8:9] nt
	s_add_u32 s8, s8, 0x10000
	s_addc_u32 s9, s9, 0
	global_load_dwordx4 v[12:15], v32, s[8:9] nt
	s_add_u32 s8, s8, 0x10000
	s_addc_u32 s9, s9, 0
	global_load_dwordx4 v[16:19], v32, s[8:9] nt
	s_add_u32 s8, s8, 0x10000
	s_addc_u32 s9, s9, 0
	global_load_dwordx4 v[20:23], v32, s[8:9] nt
	s_add_u32 s8, s8, 0x10000
	s_addc_u32 s9, s9, 0
	global_load_dwordx4 v[24:27], v32, s[8:9] nt
	s_add_u32 s8, s8, 0x10000
	s_addc_u32 s9, s9, 0
	global_load_dwordx4 v[28:31], v32, s[8:9] nt
	s_add_i32 s13, s12, 16
	s_lshr_b32 s16, s13, 3
	s_and_b32 s17, s13, 7
	s_lshl_b32 s18, s16, 19
	s_lshl_b32 s19, s80, 13
	s_add_i32 s18, s18, s19
	s_lshl_b32 s19, s17, 10
	s_add_i32 s18, s18, s19
	s_add_u32 s8, s4, s18
	s_addc_u32 s9, s5, 0
	s_mul_i32 s18, s17, 0x100000
	s_lshl_b32 s19, s16, 7
	s_add_i32 s18, s18, s19
	s_mov_b32 s21, s18
	global_load_dwordx4 v[48:51], v32, s[8:9] nt
	s_add_u32 s8, s8, 0x10000
	s_addc_u32 s9, s9, 0
	global_load_dwordx4 v[52:55], v32, s[8:9] nt
	s_add_u32 s8, s8, 0x10000
	s_addc_u32 s9, s9, 0
	global_load_dwordx4 v[56:59], v32, s[8:9] nt
	s_add_u32 s8, s8, 0x10000
	s_addc_u32 s9, s9, 0
	global_load_dwordx4 v[60:63], v32, s[8:9] nt
	s_add_u32 s8, s8, 0x10000
	s_addc_u32 s9, s9, 0
	global_load_dwordx4 v[64:67], v32, s[8:9] nt
	s_add_u32 s8, s8, 0x10000
	s_addc_u32 s9, s9, 0
	global_load_dwordx4 v[68:71], v32, s[8:9] nt
	s_add_u32 s8, s8, 0x10000
	s_addc_u32 s9, s9, 0
	global_load_dwordx4 v[72:75], v32, s[8:9] nt
	s_add_u32 s8, s8, 0x10000
	s_addc_u32 s9, s9, 0
	global_load_dwordx4 v[76:79], v32, s[8:9] nt
.Lmy_cv3_loop:
.Lmy_cv3_b0:
	s_add_i32 s13, s12, 32
	s_cmpk_lt_i32 s13, 256
	s_cbranch_scc0 .Lmy_cv3_b0_no2
	s_lshr_b32 s16, s13, 3
	s_and_b32 s17, s13, 7
	s_lshl_b32 s18, s16, 19
	s_lshl_b32 s19, s80, 13
	s_add_i32 s18, s18, s19
	s_lshl_b32 s19, s17, 10
	s_add_i32 s18, s18, s19
	s_add_u32 s8, s4, s18
	s_addc_u32 s9, s5, 0
	s_mul_i32 s18, s17, 0x100000
	s_lshl_b32 s19, s16, 7
	s_add_i32 s18, s18, s19
	s_mov_b32 s23, s18
	global_load_dwordx4 v[80:83], v32, s[8:9] nt
	s_add_u32 s8, s8, 0x10000
	s_addc_u32 s9, s9, 0
	global_load_dwordx4 v[84:87], v32, s[8:9] nt
	s_add_u32 s8, s8, 0x10000
	s_addc_u32 s9, s9, 0
	global_load_dwordx4 v[88:91], v32, s[8:9] nt
	s_add_u32 s8, s8, 0x10000
	s_addc_u32 s9, s9, 0
	global_load_dwordx4 v[92:95], v32, s[8:9] nt
	s_add_u32 s8, s8, 0x10000
	s_addc_u32 s9, s9, 0
	global_load_dwordx4 v[96:99], v32, s[8:9] nt
	s_add_u32 s8, s8, 0x10000
	s_addc_u32 s9, s9, 0
	global_load_dwordx4 v[100:103], v32, s[8:9] nt
	s_add_u32 s8, s8, 0x10000
	s_addc_u32 s9, s9, 0
	global_load_dwordx4 v[104:107], v32, s[8:9] nt
	s_add_u32 s8, s8, 0x10000
	s_addc_u32 s9, s9, 0
	global_load_dwordx4 v[108:111], v32, s[8:9] nt
	s_waitcnt vmcnt(16)
	s_branch .Lmy_cv3_b0_go

; #define LAS __attribute__((address_space(3)))
; __device__ __forceinline__ void convert_tiles(const Frame& F, int tlo, int thi, int wb, int nw) {
;     ...
;     for (;;) {
; #pragma unroll
;         for (int i = 0; i < 8; ++i) { LAS float* tp = tile + (i * 8 + F.wave) * 257 + F.lane * 4; tp[0] = v[i][0]; tp[1] = v[i][1]; tp[2] = v[i][2]; tp[3] = v[i][3]; }
;         __syncthreads();
;         const int tn = t + nw; const bool more = tn < thi; TileDesc dn = d;
;         if (more) { dn = tile_desc(F, tn);
; #pragma unroll
;             for (int i = 0; i < 8; ++i) v[i] = __builtin_nontemporal_load((const f32x4*)(dn.src + (size_t)(dn.k0 + i * 8 + F.wave) * dn.ldn + dn.n0 + F.lane * 4)); }
; #pragma unroll
;         for (int it = 0; it < 4; ++it) { const int item = it * 512 + F.tid, n = item >> 3, kg = item & 7;
;             float f[8];
; #pragma unroll
;             for (int j = 0; j < 8; ++j) f[j] = tile[(kg * 8 + j) * 257 + n];
;             const int nn = d.n0 + n; const int row = d.kind == 0 ? nn : (((nn >> 7) << 8) + (nn & 127) + (d.kind == 2 ? 128 : 0));
;             *(u32x4*)(d.dst + (size_t)row * d.K + d.k0 + kg * 8) = pack8(f); }
;         __syncthreads();
;         if (!more) break;
;         t = tn; d = dn;
;     }
.Lmy_cv3_b0_go:
	ds_write_b32 v33, v0 offset:0
	ds_write_b32 v33, v1 offset:4
	ds_write_b32 v33, v2 offset:8
	ds_write_b32 v33, v3 offset:12
	ds_write_b32 v33, v4 offset:8224
	ds_write_b32 v33, v5 offset:8228
	ds_write_b32 v33, v6 offset:8232
	ds_write_b32 v33, v7 offset:8236
	ds_write_b32 v33, v8 offset:16448
	ds_write_b32 v33, v9 offset:16452
	ds_write_b32 v33, v10 offset:16456
	ds_write_b32 v33, v11 offset:16460
	ds_write_b32 v33, v12 offset:24672
	ds_write_b32 v33, v13 offset:24676
	ds_write_b32 v33, v14 offset:24680
	ds_write_b32 v33, v15 offset:24684
	ds_write_b32 v33, v16 offset:32896
	ds_write_b32 v33, v17 offset:32900
	ds_write_b32 v33, v18 offset:32904
	ds_write_b32 v33, v19 offset:32908
	ds_write_b32 v33, v20 offset:41120
	ds_write_b32 v33, v21 offset:41124
	ds_write_b32 v33, v22 offset:41128
	ds_write_b32 v33, v23 offset:41132
	ds_write_b32 v33, v24 offset:49344
	ds_write_b32 v33, v25 offset:49348
	ds_write_b32 v33, v26 offset:49352
	ds_write_b32 v33, v27 offset:49356
	ds_write_b32 v33, v28 offset:57568
	ds_write_b32 v33, v29 offset:57572
	ds_write_b32 v33, v30 offset:57576
	ds_write_b32 v33, v31 offset:57580
	s_waitcnt lgkmcnt(0)
	s_barrier
	s_add_u32 s10, s6, s20
	s_addc_u32 s11, s7, 0
	ds_read_b32 v36, v34 offset:0
	ds_read_b32 v37, v34 offset:1028
	ds_read_b32 v38, v34 offset:2056
	ds_read_b32 v39, v34 offset:3084
	ds_read_b32 v40, v34 offset:4112
	ds_read_b32 v41, v34 offset:5140
	ds_read_b32 v42, v34 offset:6168
	ds_read_b32 v43, v34 offset:7196
	s_waitcnt lgkmcnt(0)
	v_cvt_pk_bf16_f32 v44, v36, v37
	v_cvt_pk_bf16_f32 v45, v38, v39
	v_cvt_pk_bf16_f32 v46, v40, v41
	v_cvt_pk_bf16_f32 v47, v42, v43
	global_store_dwordx4 v35, v[44:47], s[10:11]
	s_add_u32 s10, s10, 0x40000
	s_addc_u32 s11, s11, 0
	ds_read_b32 v36, v34 offset:256
	ds_read_b32 v37, v34 offset:1284
	ds_read_b32 v38, v34 offset:2312
	ds_read_b32 v39, v34 offset:3340
	ds_read_b32 v40, v34 offset:4368
	ds_read_b32 v41, v34 offset:5396
	ds_read_b32 v42, v34 offset:6424
	ds_read_b32 v43, v34 offset:7452
	s_waitcnt lgkmcnt(0)
	v_cvt_pk_bf16_f32 v44, v36, v37
	v_cvt_pk_bf16_f32 v45, v38, v39
	v_cvt_pk_bf16_f32 v46, v40, v41
	v_cvt_pk_bf16_f32 v47, v42, v43
	global_store_dwordx4 v35, v[44:47], s[10:11]
	s_add_u32 s10, s10, 0x40000
	s_addc_u32 s11, s11, 0
	ds_read_b32 v36, v34 offset:512
	ds_read_b32 v37, v34 offset:1540
	ds_read_b32 v38, v34 offset:2568
	ds_read_b32 v39, v34 offset:3596
	ds_read_b32 v40, v34 offset:4624
	ds_read_b32 v41, v34 offset:5652
	ds_read_b32 v42, v34 offset:6680
	ds_read_b32 v43, v34 offset:7708
	s_waitcnt lgkmcnt(0)
	v_cvt_pk_bf16_f32 v44, v36, v37
	v_cvt_pk_bf16_f32 v45, v38, v39
	v_cvt_pk_bf16_f32 v46, v40, v41
	v_cvt_pk_bf16_f32 v47, v42, v43
	global_store_dwordx4 v35, v[44:47], s[10:11]
	s_add_u32 s10, s10, 0x40000
	s_addc_u32 s11, s11, 0
	ds_read_b32 v36, v34 offset:768
	ds_read_b32 v37, v34 offset:1796
	ds_read_b32 v38, v34 offset:2824
	ds_read_b32 v39, v34 offset:3852
	ds_read_b32 v40, v34 offset:4880
	ds_read_b32 v41, v34 offset:5908
	ds_read_b32 v42, v34 offset:6936
	ds_read_b32 v43, v34 offset:7964
	s_waitcnt lgkmcnt(0)
	v_cvt_pk_bf16_f32 v44, v36, v37
	v_cvt_pk_bf16_f32 v45, v38, v39
	v_cvt_pk_bf16_f32 v46, v40, v41
	v_cvt_pk_bf16_f32 v47, v42, v43
	global_store_dwordx4 v35, v[44:47], s[10:11]
	s_barrier
	s_add_i32 s12, s12, 16
	s_cmpk_lt_i32 s12, 256
	s_cbranch_scc0 .Lmy_cv3_end
	s_mov_b32 s20, s21
	s_mov_b32 s21, s23
.Lmy_cv3_b1:
	s_add_i32 s13, s12, 32
	s_cmpk_lt_i32 s13, 256
	s_cbranch_scc0 .Lmy_cv3_b1_no2
	s_lshr_b32 s16, s13, 3
	s_and_b32 s17, s13, 7
	s_lshl_b32 s18, s16, 19
	s_lshl_b32 s19, s80, 13
	s_add_i32 s18, s18, s19
	s_lshl_b32 s19, s17, 10
	s_add_i32 s18, s18, s19
	s_add_u32 s8, s4, s18
	s_addc_u32 s9, s5, 0
	s_mul_i32 s18, s17, 0x100000
	s_lshl_b32 s19, s16, 7
	s_add_i32 s18, s18, s19
	s_mov_b32 s23, s18
	global_load_dwordx4 v[0:3], v32, s[8:9] nt
	s_add_u32 s8, s8, 0x10000
	s_addc_u32 s9, s9, 0
	global_load_dwordx4 v[4:7], v32, s[8:9] nt
	s_add_u32 s8, s8, 0x10000
	s_addc_u32 s9, s9, 0
	global_load_dwordx4 v[8:11], v32, s[8:9] nt
	s_add_u32 s8, s8, 0x10000
	s_addc_u32 s9, s9, 0
	global_load_dwordx4 v[12:15], v32, s[8:9] nt
	s_add_u32 s8, s8, 0x10000
	s_addc_u32 s9, s9, 0
	global_load_dwordx4 v[16:19], v32, s[8:9] nt
	s_add_u32 s8, s8, 0x10000
	s_addc_u32 s9, s9, 0
	global_load_dwordx4 v[20:23], v32, s[8:9] nt
	s_add_u32 s8, s8, 0x10000
	s_addc_u32 s9, s9, 0
	global_load_dwordx4 v[24:27], v32, s[8:9] nt
	s_add_u32 s8, s8, 0x10000
	s_addc_u32 s9, s9, 0
	global_load_dwordx4 v[28:31], v32, s[8:9] nt
	s_waitcnt vmcnt(16)
	s_branch .Lmy_cv3_b1_go

; #define LAS __attribute__((address_space(3)))
; __device__ __forceinline__ void convert_tiles(const Frame& F, int tlo, int thi, int wb, int nw) {
;     ...
;     for (;;) {
; #pragma unroll
;         for (int i = 0; i < 8; ++i) { LAS float* tp = tile + (i * 8 + F.wave) * 257 + F.lane * 4; tp[0] = v[i][0]; tp[1] = v[i][1]; tp[2] = v[i][2]; tp[3] = v[i][3]; }
;         __syncthreads();
;         const int tn = t + nw; const bool more = tn < thi; TileDesc dn = d;
;         if (more) { dn = tile_desc(F, tn);
; #pragma unroll
;             for (int i = 0; i < 8; ++i) v[i] = __builtin_nontemporal_load((const f32x4*)(dn.src + (size_t)(dn.k0 + i * 8 + F.wave) * dn.ldn + dn.n0 + F.lane * 4)); }
; #pragma unroll
;         for (int it = 0; it < 4; ++it) { const int item = it * 512 + F.tid, n = item >> 3, kg = item & 7;
;             float f[8];
; #pragma unroll
;             for (int j = 0; j < 8; ++j) f[j] = tile[(kg * 8 + j) * 257 + n];
;             const int nn = d.n0 + n; const int row = d.kind == 0 ? nn : (((nn >> 7) << 8) + (nn & 127) + (d.kind == 2 ? 128 : 0));
;             *(u32x4*)(d.dst + (size_t)row * d.K + d.k0 + kg * 8) = pack8(f); }
;         __syncthreads();
;         if (!more) break;
;         t = tn; d = dn;
;     }
.Lmy_cv3_b1_go:
	ds_write_b32 v33, v48 offset:0
	ds_write_b32 v33, v49 offset:4
	ds_write_b32 v33, v50 offset:8
	ds_write_b32 v33, v51 offset:12
	ds_write_b32 v33, v52 offset:8224
	ds_write_b32 v33, v53 offset:8228
	ds_write_b32 v33, v54 offset:8232
	ds_write_b32 v33, v55 offset:8236
	ds_write_b32 v33, v56 offset:16448
	ds_write_b32 v33, v57 offset:16452
	ds_write_b32 v33, v58 offset:16456
	ds_write_b32 v33, v59 offset:16460
	ds_write_b32 v33, v60 offset:24672
	ds_write_b32 v33, v61 offset:24676
	ds_write_b32 v33, v62 offset:24680
	ds_write_b32 v33, v63 offset:24684
	ds_write_b32 v33, v64 offset:32896
	ds_write_b32 v33, v65 offset:32900
	ds_write_b32 v33, v66 offset:32904
	ds_write_b32 v33, v67 offset:32908
	ds_write_b32 v33, v68 offset:41120
	ds_write_b32 v33, v69 offset:41124
	ds_write_b32 v33, v70 offset:41128
	ds_write_b32 v33, v71 offset:41132
	ds_write_b32 v33, v72 offset:49344
	ds_write_b32 v33, v73 offset:49348
	ds_write_b32 v33, v74 offset:49352
	ds_write_b32 v33, v75 offset:49356
	ds_write_b32 v33, v76 offset:57568
	ds_write_b32 v33, v77 offset:57572
	ds_write_b32 v33, v78 offset:57576
	ds_write_b32 v33, v79 offset:57580
	s_waitcnt lgkmcnt(0)
	s_barrier
	s_add_u32 s10, s6, s20
	s_addc_u32 s11, s7, 0
	ds_read_b32 v36, v34 offset:0
	ds_read_b32 v37, v34 offset:1028
	ds_read_b32 v38, v34 offset:2056
	ds_read_b32 v39, v34 offset:3084
	ds_read_b32 v40, v34 offset:4112
	ds_read_b32 v41, v34 offset:5140
	ds_read_b32 v42, v34 offset:6168
	ds_read_b32 v43, v34 offset:7196
	s_waitcnt lgkmcnt(0)
	v_cvt_pk_bf16_f32 v44, v36, v37
	v_cvt_pk_bf16_f32 v45, v38, v39
	v_cvt_pk_bf16_f32 v46, v40, v41
	v_cvt_pk_bf16_f32 v47, v42, v43
	global_store_dwordx4 v35, v[44:47], s[10:11]
	s_add_u32 s10, s10, 0x40000
	s_addc_u32 s11, s11, 0
	ds_read_b32 v36, v34 offset:256
	ds_read_b32 v37, v34 offset:1284
	ds_read_b32 v38, v34 offset:2312
	ds_read_b32 v39, v34 offset:3340
	ds_read_b32 v40, v34 offset:4368
	ds_read_b32 v41, v34 offset:5396
	ds_read_b32 v42, v34 offset:6424
	ds_read_b32 v43, v34 offset:7452
	s_waitcnt lgkmcnt(0)
	v_cvt_pk_bf16_f32 v44, v36, v37
	v_cvt_pk_bf16_f32 v45, v38, v39
	v_cvt_pk_bf16_f32 v46, v40, v41
	v_cvt_pk_bf16_f32 v47, v42, v43
	global_store_dwordx4 v35, v[44:47], s[10:11]
	s_add_u32 s10, s10, 0x40000
	s_addc_u32 s11, s11, 0
	ds_read_b32 v36, v34 offset:512
	ds_read_b32 v37, v34 offset:1540
	ds_read_b32 v38, v34 offset:2568
	ds_read_b32 v39, v34 offset:3596
	ds_read_b32 v40, v34 offset:4624
	ds_read_b32 v41, v34 offset:5652
	ds_read_b32 v42, v34 offset:6680
	ds_read_b32 v43, v34 offset:7708
	s_waitcnt lgkmcnt(0)
	v_cvt_pk_bf16_f32 v44, v36, v37
	v_cvt_pk_bf16_f32 v45, v38, v39
	v_cvt_pk_bf16_f32 v46, v40, v41
	v_cvt_pk_bf16_f32 v47, v42, v43
	global_store_dwordx4 v35, v[44:47], s[10:11]
	s_add_u32 s10, s10, 0x40000
	s_addc_u32 s11, s11, 0
	ds_read_b32 v36, v34 offset:768
	ds_read_b32 v37, v34 offset:1796
	ds_read_b32 v38, v34 offset:2824
	ds_read_b32 v39, v34 offset:3852
	ds_read_b32 v40, v34 offset:4880
	ds_read_b32 v41, v34 offset:5908
	ds_read_b32 v42, v34 offset:6936
	ds_read_b32 v43, v34 offset:7964
	s_waitcnt lgkmcnt(0)
	v_cvt_pk_bf16_f32 v44, v36, v37
	v_cvt_pk_bf16_f32 v45, v38, v39
	v_cvt_pk_bf16_f32 v46, v40, v41
	v_cvt_pk_bf16_f32 v47, v42, v43
	global_store_dwordx4 v35, v[44:47], s[10:11]
	s_barrier
	s_add_i32 s12, s12, 16
	s_cmpk_lt_i32 s12, 256
	s_cbranch_scc0 .Lmy_cv3_end
	s_mov_b32 s20, s21
	s_mov_b32 s21, s23
.Lmy_cv3_b2:
	s_add_i32 s13, s12, 32
	s_cmpk_lt_i32 s13, 256
	s_cbranch_scc0 .Lmy_cv3_b2_no2
	s_lshr_b32 s16, s13, 3
	s_and_b32 s17, s13, 7
	s_lshl_b32 s18, s16, 19
	s_lshl_b32 s19, s80, 13
	s_add_i32 s18, s18, s19
	s_lshl_b32 s19, s17, 10
	s_add_i32 s18, s18, s19
	s_add_u32 s8, s4, s18
	s_addc_u32 s9, s5, 0
	s_mul_i32 s18, s17, 0x100000
	s_lshl_b32 s19, s16, 7
	s_add_i32 s18, s18, s19
	s_mov_b32 s23, s18
	global_load_dwordx4 v[48:51], v32, s[8:9] nt
	s_add_u32 s8, s8, 0x10000
	s_addc_u32 s9, s9, 0
	global_load_dwordx4 v[52:55], v32, s[8:9] nt
	s_add_u32 s8, s8, 0x10000
	s_addc_u32 s9, s9, 0
	global_load_dwordx4 v[56:59], v32, s[8:9] nt
	s_add_u32 s8, s8, 0x10000
	s_addc_u32 s9, s9, 0
	global_load_dwordx4 v[60:63], v32, s[8:9] nt
	s_add_u32 s8, s8, 0x10000
	s_addc_u32 s9, s9, 0
	global_load_dwordx4 v[64:67], v32, s[8:9] nt
	s_add_u32 s8, s8, 0x10000
	s_addc_u32 s9, s9, 0
	global_load_dwordx4 v[68:71], v32, s[8:9] nt
	s_add_u32 s8, s8, 0x10000
	s_addc_u32 s9, s9, 0
	global_load_dwordx4 v[72:75], v32, s[8:9] nt
	s_add_u32 s8, s8, 0x10000
	s_addc_u32 s9, s9, 0
	global_load_dwordx4 v[76:79], v32, s[8:9] nt
	s_waitcnt vmcnt(16)
	s_branch .Lmy_cv3_b2_go

; #define LAS __attribute__((address_space(3)))
; __device__ __forceinline__ void convert_tiles(const Frame& F, int tlo, int thi, int wb, int nw) {
;     ...
;     for (;;) {
; #pragma unroll
;         for (int i = 0; i < 8; ++i) { LAS float* tp = tile + (i * 8 + F.wave) * 257 + F.lane * 4; tp[0] = v[i][0]; tp[1] = v[i][1]; tp[2] = v[i][2]; tp[3] = v[i][3]; }
;         __syncthreads();
;         const int tn = t + nw; const bool more = tn < thi; TileDesc dn = d;
;         if (more) { dn = tile_desc(F, tn);
; #pragma unroll
;             for (int i = 0; i < 8; ++i) v[i] = __builtin_nontemporal_load((const f32x4*)(dn.src + (size_t)(dn.k0 + i * 8 + F.wave) * dn.ldn + dn.n0 + F.lane * 4)); }
; #pragma unroll
;         for (int it = 0; it < 4; ++it) { const int item = it * 512 + F.tid, n = item >> 3, kg = item & 7;
;             float f[8];
; #pragma unroll
;             for (int j = 0; j < 8; ++j) f[j] = tile[(kg * 8 + j) * 257 + n];
;             const int nn = d.n0 + n; const int row = d.kind == 0 ? nn : (((nn >> 7) << 8) + (nn & 127) + (d.kind == 2 ? 128 : 0));
;             *(u32x4*)(d.dst + (size_t)row * d.K + d.k0 + kg * 8) = pack8(f); }
;         __syncthreads();
;         if (!more) break;
;         t = tn; d = dn;
;     }
.Lmy_cv3_b2_go:
	ds_write_b32 v33, v80 offset:0
	ds_write_b32 v33, v81 offset:4
	ds_write_b32 v33, v82 offset:8
	ds_write_b32 v33, v83 offset:12
	ds_write_b32 v33, v84 offset:8224
	ds_write_b32 v33, v85 offset:8228
	ds_write_b32 v33, v86 offset:8232
	ds_write_b32 v33, v87 offset:8236
	ds_write_b32 v33, v88 offset:16448
	ds_write_b32 v33, v89 offset:16452
	ds_write_b32 v33, v90 offset:16456
	ds_write_b32 v33, v91 offset:16460
	ds_write_b32 v33, v92 offset:24672
	ds_write_b32 v33, v93 offset:24676
	ds_write_b32 v33, v94 offset:24680
	ds_write_b32 v33, v95 offset:24684
	ds_write_b32 v33, v96 offset:32896
	ds_write_b32 v33, v97 offset:32900
	ds_write_b32 v33, v98 offset:32904
	ds_write_b32 v33, v99 offset:32908
	ds_write_b32 v33, v100 offset:41120
	ds_write_b32 v33, v101 offset:41124
	ds_write_b32 v33, v102 offset:41128
	ds_write_b32 v33, v103 offset:41132
	ds_write_b32 v33, v104 offset:49344
	ds_write_b32 v33, v105 offset:49348
	ds_write_b32 v33, v106 offset:49352
	ds_write_b32 v33, v107 offset:49356
	ds_write_b32 v33, v108 offset:57568
	ds_write_b32 v33, v109 offset:57572
	ds_write_b32 v33, v110 offset:57576
	ds_write_b32 v33, v111 offset:57580
	s_waitcnt lgkmcnt(0)
	s_barrier
	s_add_u32 s10, s6, s20
	s_addc_u32 s11, s7, 0
	ds_read_b32 v36, v34 offset:0
	ds_read_b32 v37, v34 offset:1028
	ds_read_b32 v38, v34 offset:2056
	ds_read_b32 v39, v34 offset:3084
	ds_read_b32 v40, v34 offset:4112
	ds_read_b32 v41, v34 offset:5140
	ds_read_b32 v42, v34 offset:6168
	ds_read_b32 v43, v34 offset:7196
	s_waitcnt lgkmcnt(0)
	v_cvt_pk_bf16_f32 v44, v36, v37
	v_cvt_pk_bf16_f32 v45, v38, v39
	v_cvt_pk_bf16_f32 v46, v40, v41
	v_cvt_pk_bf16_f32 v47, v42, v43
	global_store_dwordx4 v35, v[44:47], s[10:11]
	s_add_u32 s10, s10, 0x40000
	s_addc_u32 s11, s11, 0
	ds_read_b32 v36, v34 offset:256
	ds_read_b32 v37, v34 offset:1284
	ds_read_b32 v38, v34 offset:2312
	ds_read_b32 v39, v34 offset:3340
	ds_read_b32 v40, v34 offset:4368
	ds_read_b32 v41, v34 offset:5396
	ds_read_b32 v42, v34 offset:6424
	ds_read_b32 v43, v34 offset:7452
	s_waitcnt lgkmcnt(0)
	v_cvt_pk_bf16_f32 v44, v36, v37
	v_cvt_pk_bf16_f32 v45, v38, v39
	v_cvt_pk_bf16_f32 v46, v40, v41
	v_cvt_pk_bf16_f32 v47, v42, v43
	global_store_dwordx4 v35, v[44:47], s[10:11]
	s_add_u32 s10, s10, 0x40000
	s_addc_u32 s11, s11, 0
	ds_read_b32 v36, v34 offset:512
	ds_read_b32 v37, v34 offset:1540
	ds_read_b32 v38, v34 offset:2568
	ds_read_b32 v39, v34 offset:3596
	ds_read_b32 v40, v34 offset:4624
	ds_read_b32 v41, v34 offset:5652
	ds_read_b32 v42, v34 offset:6680
	ds_read_b32 v43, v34 offset:7708
	s_waitcnt lgkmcnt(0)
	v_cvt_pk_bf16_f32 v44, v36, v37
	v_cvt_pk_bf16_f32 v45, v38, v39
	v_cvt_pk_bf16_f32 v46, v40, v41
	v_cvt_pk_bf16_f32 v47, v42, v43
	global_store_dwordx4 v35, v[44:47], s[10:11]
	s_add_u32 s10, s10, 0x40000
	s_addc_u32 s11, s11, 0
	ds_read_b32 v36, v34 offset:768
	ds_read_b32 v37, v34 offset:1796
	ds_read_b32 v38, v34 offset:2824
	ds_read_b32 v39, v34 offset:3852
	ds_read_b32 v40, v34 offset:4880
	ds_read_b32 v41, v34 offset:5908
	ds_read_b32 v42, v34 offset:6936
	ds_read_b32 v43, v34 offset:7964
	s_waitcnt lgkmcnt(0)
	v_cvt_pk_bf16_f32 v44, v36, v37
	v_cvt_pk_bf16_f32 v45, v38, v39
	v_cvt_pk_bf16_f32 v46, v40, v41
	v_cvt_pk_bf16_f32 v47, v42, v43
	global_store_dwordx4 v35, v[44:47], s[10:11]
	s_barrier
	s_add_i32 s12, s12, 16
	s_cmpk_lt_i32 s12, 256
	s_cbranch_scc0 .Lmy_cv3_end
	s_mov_b32 s20, s21
	s_mov_b32 s21, s23
	s_branch .Lmy_cv3_loop

; #define LAS __attribute__((address_space(3)))
; __device__ __forceinline__ void convert_tiles(const Frame& F, int tlo, int thi, int wb, int nw) {
;     LAS float* tile = (LAS float*)F.lds;
;     int t = tlo + wb; if (t >= thi) return;
;     TileDesc d = tile_desc(F, t);
;     f32x4 v[8];
; #pragma unroll
;     for (int i = 0; i < 8; ++i) v[i] = __builtin_nontemporal_load((const f32x4*)(d.src + (size_t)(d.k0 + i * 8 + F.wave) * d.ldn + d.n0 + F.lane * 4));
;     for (;;) {
; #pragma unroll
;         for (int i = 0; i < 8; ++i) { LAS float* tp = tile + (i * 8 + F.wave) * 257 + F.lane * 4; tp[0] = v[i][0]; tp[1] = v[i][1]; tp[2] = v[i][2]; tp[3] = v[i][3]; }
;         __syncthreads();
;         const int tn = t + nw; const bool more = tn < thi; TileDesc dn = d;
;         if (more) { dn = tile_desc(F, tn);
; #pragma unroll
;             for (int i = 0; i < 8; ++i) v[i] = __builtin_nontemporal_load((const f32x4*)(dn.src + (size_t)(dn.k0 + i * 8 + F.wave) * dn.ldn + dn.n0 + F.lane * 4)); }
.LBB0_1034:
	s_waitcnt vmcnt(0)
	s_barrier
	s_cmpk_lt_i32 s33, 216
	s_cbranch_scc1 .Lmy_cv9_end
	s_sub_i32 s12, s33, 216
	s_cmpk_ge_i32 s12, 40
	s_cbranch_scc1 .Lmy_cv9_end
	s_add_i32 s12, s12, 0
	s_load_dwordx2 s[4:5], s[98:99], 0xb0
	s_add_u32 s6, s84, 0x7a00000
	s_addc_u32 s7, s85, 0
	v_lshlrev_b32_e32 v32, 4, v160
	s_mul_i32 s16, s80, 0x404
	v_add_u32_e32 v33, s16, v32
	v_and_b32_e32 v36, 7, v144
	v_lshrrev_b32_e32 v35, 3, v144
	v_mul_u32_u24_e32 v34, 0x2020, v36
	v_lshl_add_u32 v34, v35, 2, v34
	v_mov_b32_e32 v37, 0x2c00
	v_mul_u32_u24_e32 v35, v35, v37
	v_lshl_add_u32 v35, v36, 4, v35
	s_waitcnt lgkmcnt(0)
	s_lshr_b32 s16, s12, 3
	s_and_b32 s17, s12, 7
	s_lshl_b32 s18, s16, 19
	s_lshl_b32 s19, s80, 13
	s_add_i32 s18, s18, s19
	s_lshl_b32 s19, s17, 10
	s_add_i32 s18, s18, s19
	s_add_u32 s8, s4, s18
	s_addc_u32 s9, s5, 0
	s_mul_i32 s18, s17, 0x2c0000
	s_lshl_b32 s19, s16, 7
	s_add_i32 s18, s18, s19
	s_mov_b32 s20, s18
	global_load_dwordx4 v[0:3], v32, s[8:9] nt
	s_add_u32 s8, s8, 0x10000
	s_addc_u32 s9, s9, 0
	global_load_dwordx4 v[4:7], v32, s[8:9] nt
	s_add_u32 s8, s8, 0x10000
	s_addc_u32 s9, s9, 0
	global_load_dwordx4 v[8:11], v32, s[8:9] nt
	s_add_u32 s8, s8, 0x10000
	s_addc_u32 s9, s9, 0
	global_load_dwordx4 v[12:15], v32, s[8:9] nt
	s_add_u32 s8, s8, 0x10000
	s_addc_u32 s9, s9, 0
	global_load_dwordx4 v[16:19], v32, s[8:9] nt
	s_add_u32 s8, s8, 0x10000
	s_addc_u32 s9, s9, 0
	global_load_dwordx4 v[20:23], v32, s[8:9] nt
	s_add_u32 s8, s8, 0x10000
	s_addc_u32 s9, s9, 0
	global_load_dwordx4 v[24:27], v32, s[8:9] nt
	s_add_u32 s8, s8, 0x10000
	s_addc_u32 s9, s9, 0
	global_load_dwordx4 v[28:31], v32, s[8:9] nt
	s_add_i32 s13, s12, 40
	s_lshr_b32 s16, s13, 3
	s_and_b32 s17, s13, 7
	s_lshl_b32 s18, s16, 19
	s_lshl_b32 s19, s80, 13
	s_add_i32 s18, s18, s19
	s_lshl_b32 s19, s17, 10
	s_add_i32 s18, s18, s19
	s_add_u32 s8, s4, s18
	s_addc_u32 s9, s5, 0
	s_mul_i32 s18, s17, 0x2c0000
	s_lshl_b32 s19, s16, 7
	s_add_i32 s18, s18, s19
	s_mov_b32 s21, s18
	global_load_dwordx4 v[48:51], v32, s[8:9] nt
	s_add_u32 s8, s8, 0x10000
	s_addc_u32 s9, s9, 0
	global_load_dwordx4 v[52:55], v32, s[8:9] nt
	s_add_u32 s8, s8, 0x10000
	s_addc_u32 s9, s9, 0
	global_load_dwordx4 v[56:59], v32, s[8:9] nt
	s_add_u32 s8, s8, 0x10000
	s_addc_u32 s9, s9, 0
	global_load_dwordx4 v[60:63], v32, s[8:9] nt
	s_add_u32 s8, s8, 0x10000
	s_addc_u32 s9, s9, 0
	global_load_dwordx4 v[64:67], v32, s[8:9] nt
	s_add_u32 s8, s8, 0x10000
	s_addc_u32 s9, s9, 0
	global_load_dwordx4 v[68:71], v32, s[8:9] nt
	s_add_u32 s8, s8, 0x10000
	s_addc_u32 s9, s9, 0
	global_load_dwordx4 v[72:75], v32, s[8:9] nt
	s_add_u32 s8, s8, 0x10000
	s_addc_u32 s9, s9, 0
	global_load_dwordx4 v[76:79], v32, s[8:9] nt
.Lmy_cv9_loop:
.Lmy_cv9_b0:
	s_add_i32 s13, s12, 80
	s_cmpk_lt_i32 s13, 704
	s_cbranch_scc0 .Lmy_cv9_b0_no2
	s_lshr_b32 s16, s13, 3
	s_and_b32 s17, s13, 7
	s_lshl_b32 s18, s16, 19
	s_lshl_b32 s19, s80, 13
	s_add_i32 s18, s18, s19
	s_lshl_b32 s19, s17, 10
	s_add_i32 s18, s18, s19
	s_add_u32 s8, s4, s18
	s_addc_u32 s9, s5, 0
	s_mul_i32 s18, s17, 0x2c0000
	s_lshl_b32 s19, s16, 7
	s_add_i32 s18, s18, s19
	s_mov_b32 s23, s18
	global_load_dwordx4 v[80:83], v32, s[8:9] nt
	s_add_u32 s8, s8, 0x10000
	s_addc_u32 s9, s9, 0
	global_load_dwordx4 v[84:87], v32, s[8:9] nt
	s_add_u32 s8, s8, 0x10000
	s_addc_u32 s9, s9, 0
	global_load_dwordx4 v[88:91], v32, s[8:9] nt
	s_add_u32 s8, s8, 0x10000
	s_addc_u32 s9, s9, 0
	global_load_dwordx4 v[92:95], v32, s[8:9] nt
	s_add_u32 s8, s8, 0x10000
	s_addc_u32 s9, s9, 0
	global_load_dwordx4 v[96:99], v32, s[8:9] nt
	s_add_u32 s8, s8, 0x10000
	s_addc_u32 s9, s9, 0
	global_load_dwordx4 v[100:103], v32, s[8:9] nt
	s_add_u32 s8, s8, 0x10000
	s_addc_u32 s9, s9, 0
	global_load_dwordx4 v[104:107], v32, s[8:9] nt
	s_add_u32 s8, s8, 0x10000
	s_addc_u32 s9, s9, 0
	global_load_dwordx4 v[108:111], v32, s[8:9] nt
	s_waitcnt vmcnt(16)
	s_branch .Lmy_cv9_b0_go

; #define LAS __attribute__((address_space(3)))
; __device__ __forceinline__ void convert_tiles(const Frame& F, int tlo, int thi, int wb, int nw) {
;     ...
;     for (;;) {
; #pragma unroll
;         for (int i = 0; i < 8; ++i) { LAS float* tp = tile + (i * 8 + F.wave) * 257 + F.lane * 4; tp[0] = v[i][0]; tp[1] = v[i][1]; tp[2] = v[i][2]; tp[3] = v[i][3]; }
;         __syncthreads();
;         const int tn = t + nw; const bool more = tn < thi; TileDesc dn = d;
;         if (more) { dn = tile_desc(F, tn);
; #pragma unroll
;             for (int i = 0; i < 8; ++i) v[i] = __builtin_nontemporal_load((const f32x4*)(dn.src + (size_t)(dn.k0 + i * 8 + F.wave) * dn.ldn + dn.n0 + F.lane * 4)); }
; #pragma unroll
;         for (int it = 0; it < 4; ++it) { const int item = it * 512 + F.tid, n = item >> 3, kg = item & 7;
;             float f[8];
; #pragma unroll
;             for (int j = 0; j < 8; ++j) f[j] = tile[(kg * 8 + j) * 257 + n];
;             const int nn = d.n0 + n; const int row = d.kind == 0 ? nn : (((nn >> 7) << 8) + (nn & 127) + (d.kind == 2 ? 128 : 0));
;             *(u32x4*)(d.dst + (size_t)row * d.K + d.k0 + kg * 8) = pack8(f); }
;         __syncthreads();
;         if (!more) break;
;         t = tn; d = dn;
;     }
.Lmy_cv9_b0_go:
	ds_write_b32 v33, v0 offset:0
	ds_write_b32 v33, v1 offset:4
	ds_write_b32 v33, v2 offset:8
	ds_write_b32 v33, v3 offset:12
	ds_write_b32 v33, v4 offset:8224
	ds_write_b32 v33, v5 offset:8228
	ds_write_b32 v33, v6 offset:8232
	ds_write_b32 v33, v7 offset:8236
	ds_write_b32 v33, v8 offset:16448
	ds_write_b32 v33, v9 offset:16452
	ds_write_b32 v33, v10 offset:16456
	ds_write_b32 v33, v11 offset:16460
	ds_write_b32 v33, v12 offset:24672
	ds_write_b32 v33, v13 offset:24676
	ds_write_b32 v33, v14 offset:24680
	ds_write_b32 v33, v15 offset:24684
	ds_write_b32 v33, v16 offset:32896
	ds_write_b32 v33, v17 offset:32900
	ds_write_b32 v33, v18 offset:32904
	ds_write_b32 v33, v19 offset:32908
	ds_write_b32 v33, v20 offset:41120
	ds_write_b32 v33, v21 offset:41124
	ds_write_b32 v33, v22 offset:41128
	ds_write_b32 v33, v23 offset:41132
	ds_write_b32 v33, v24 offset:49344
	ds_write_b32 v33, v25 offset:49348
	ds_write_b32 v33, v26 offset:49352
	ds_write_b32 v33, v27 offset:49356
	ds_write_b32 v33, v28 offset:57568
	ds_write_b32 v33, v29 offset:57572
	ds_write_b32 v33, v30 offset:57576
	ds_write_b32 v33, v31 offset:57580
	s_waitcnt lgkmcnt(0)
	s_barrier
	s_add_u32 s10, s6, s20
	s_addc_u32 s11, s7, 0
	ds_read_b32 v36, v34 offset:0
	ds_read_b32 v37, v34 offset:1028
	ds_read_b32 v38, v34 offset:2056
	ds_read_b32 v39, v34 offset:3084
	ds_read_b32 v40, v34 offset:4112
	ds_read_b32 v41, v34 offset:5140
	ds_read_b32 v42, v34 offset:6168
	ds_read_b32 v43, v34 offset:7196
	s_waitcnt lgkmcnt(0)
	v_cvt_pk_bf16_f32 v44, v36, v37
	v_cvt_pk_bf16_f32 v45, v38, v39
	v_cvt_pk_bf16_f32 v46, v40, v41
	v_cvt_pk_bf16_f32 v47, v42, v43
	global_store_dwordx4 v35, v[44:47], s[10:11]
	s_add_u32 s10, s10, 0xb0000
	s_addc_u32 s11, s11, 0
	ds_read_b32 v36, v34 offset:256
	ds_read_b32 v37, v34 offset:1284
	ds_read_b32 v38, v34 offset:2312
	ds_read_b32 v39, v34 offset:3340
	ds_read_b32 v40, v34 offset:4368
	ds_read_b32 v41, v34 offset:5396
	ds_read_b32 v42, v34 offset:6424
	ds_read_b32 v43, v34 offset:7452
	s_waitcnt lgkmcnt(0)
	v_cvt_pk_bf16_f32 v44, v36, v37
	v_cvt_pk_bf16_f32 v45, v38, v39
	v_cvt_pk_bf16_f32 v46, v40, v41
	v_cvt_pk_bf16_f32 v47, v42, v43
	global_store_dwordx4 v35, v[44:47], s[10:11]
	s_add_u32 s10, s10, 0xb0000
	s_addc_u32 s11, s11, 0
	ds_read_b32 v36, v34 offset:512
	ds_read_b32 v37, v34 offset:1540
	ds_read_b32 v38, v34 offset:2568
	ds_read_b32 v39, v34 offset:3596
	ds_read_b32 v40, v34 offset:4624
	ds_read_b32 v41, v34 offset:5652
	ds_read_b32 v42, v34 offset:6680
	ds_read_b32 v43, v34 offset:7708
	s_waitcnt lgkmcnt(0)
	v_cvt_pk_bf16_f32 v44, v36, v37
	v_cvt_pk_bf16_f32 v45, v38, v39
	v_cvt_pk_bf16_f32 v46, v40, v41
	v_cvt_pk_bf16_f32 v47, v42, v43
	global_store_dwordx4 v35, v[44:47], s[10:11]
	s_add_u32 s10, s10, 0xb0000
	s_addc_u32 s11, s11, 0
	ds_read_b32 v36, v34 offset:768
	ds_read_b32 v37, v34 offset:1796
	ds_read_b32 v38, v34 offset:2824
	ds_read_b32 v39, v34 offset:3852
	ds_read_b32 v40, v34 offset:4880
	ds_read_b32 v41, v34 offset:5908
	ds_read_b32 v42, v34 offset:6936
	ds_read_b32 v43, v34 offset:7964
	s_waitcnt lgkmcnt(0)
	v_cvt_pk_bf16_f32 v44, v36, v37
	v_cvt_pk_bf16_f32 v45, v38, v39
	v_cvt_pk_bf16_f32 v46, v40, v41
	v_cvt_pk_bf16_f32 v47, v42, v43
	global_store_dwordx4 v35, v[44:47], s[10:11]
	s_barrier
	s_add_i32 s12, s12, 40
	s_cmpk_lt_i32 s12, 704
	s_cbranch_scc0 .Lmy_cv9_end
	s_mov_b32 s20, s21
	s_mov_b32 s21, s23
.Lmy_cv9_b1:
	s_add_i32 s13, s12, 80
	s_cmpk_lt_i32 s13, 704
	s_cbranch_scc0 .Lmy_cv9_b1_no2
	s_lshr_b32 s16, s13, 3
	s_and_b32 s17, s13, 7
	s_lshl_b32 s18, s16, 19
	s_lshl_b32 s19, s80, 13
	s_add_i32 s18, s18, s19
	s_lshl_b32 s19, s17, 10
	s_add_i32 s18, s18, s19
	s_add_u32 s8, s4, s18
	s_addc_u32 s9, s5, 0
	s_mul_i32 s18, s17, 0x2c0000
	s_lshl_b32 s19, s16, 7
	s_add_i32 s18, s18, s19
	s_mov_b32 s23, s18
	global_load_dwordx4 v[0:3], v32, s[8:9] nt
	s_add_u32 s8, s8, 0x10000
	s_addc_u32 s9, s9, 0
	global_load_dwordx4 v[4:7], v32, s[8:9] nt
	s_add_u32 s8, s8, 0x10000
	s_addc_u32 s9, s9, 0
	global_load_dwordx4 v[8:11], v32, s[8:9] nt
	s_add_u32 s8, s8, 0x10000
	s_addc_u32 s9, s9, 0
	global_load_dwordx4 v[12:15], v32, s[8:9] nt
	s_add_u32 s8, s8, 0x10000
	s_addc_u32 s9, s9, 0
	global_load_dwordx4 v[16:19], v32, s[8:9] nt
	s_add_u32 s8, s8, 0x10000
	s_addc_u32 s9, s9, 0
	global_load_dwordx4 v[20:23], v32, s[8:9] nt
	s_add_u32 s8, s8, 0x10000
	s_addc_u32 s9, s9, 0
	global_load_dwordx4 v[24:27], v32, s[8:9] nt
	s_add_u32 s8, s8, 0x10000
	s_addc_u32 s9, s9, 0
	global_load_dwordx4 v[28:31], v32, s[8:9] nt
	s_waitcnt vmcnt(16)
	s_branch .Lmy_cv9_b1_go

; #define LAS __attribute__((address_space(3)))
; __device__ __forceinline__ void convert_tiles(const Frame& F, int tlo, int thi, int wb, int nw) {
;     ...
;     for (;;) {
; #pragma unroll
;         for (int i = 0; i < 8; ++i) { LAS float* tp = tile + (i * 8 + F.wave) * 257 + F.lane * 4; tp[0] = v[i][0]; tp[1] = v[i][1]; tp[2] = v[i][2]; tp[3] = v[i][3]; }
;         __syncthreads();
;         const int tn = t + nw; const bool more = tn < thi; TileDesc dn = d;
;         if (more) { dn = tile_desc(F, tn);
; #pragma unroll
;             for (int i = 0; i < 8; ++i) v[i] = __builtin_nontemporal_load((const f32x4*)(dn.src + (size_t)(dn.k0 + i * 8 + F.wave) * dn.ldn + dn.n0 + F.lane * 4)); }
; #pragma unroll
;         for (int it = 0; it < 4; ++it) { const int item = it * 512 + F.tid, n = item >> 3, kg = item & 7;
;             float f[8];
; #pragma unroll
;             for (int j = 0; j < 8; ++j) f[j] = tile[(kg * 8 + j) * 257 + n];
;             const int nn = d.n0 + n; const int row = d.kind == 0 ? nn : (((nn >> 7) << 8) + (nn & 127) + (d.kind == 2 ? 128 : 0));
;             *(u32x4*)(d.dst + (size_t)row * d.K + d.k0 + kg * 8) = pack8(f); }
;         __syncthreads();
;         if (!more) break;
;         t = tn; d = dn;
;     }
.Lmy_cv9_b1_go:
	ds_write_b32 v33, v48 offset:0
	ds_write_b32 v33, v49 offset:4
	ds_write_b32 v33, v50 offset:8
	ds_write_b32 v33, v51 offset:12
	ds_write_b32 v33, v52 offset:8224
	ds_write_b32 v33, v53 offset:8228
	ds_write_b32 v33, v54 offset:8232
	ds_write_b32 v33, v55 offset:8236
	ds_write_b32 v33, v56 offset:16448
	ds_write_b32 v33, v57 offset:16452
	ds_write_b32 v33, v58 offset:16456
	ds_write_b32 v33, v59 offset:16460
	ds_write_b32 v33, v60 offset:24672
	ds_write_b32 v33, v61 offset:24676
	ds_write_b32 v33, v62 offset:24680
	ds_write_b32 v33, v63 offset:24684
	ds_write_b32 v33, v64 offset:32896
	ds_write_b32 v33, v65 offset:32900
	ds_write_b32 v33, v66 offset:32904
	ds_write_b32 v33, v67 offset:32908
	ds_write_b32 v33, v68 offset:41120
	ds_write_b32 v33, v69 offset:41124
	ds_write_b32 v33, v70 offset:41128
	ds_write_b32 v33, v71 offset:41132
	ds_write_b32 v33, v72 offset:49344
	ds_write_b32 v33, v73 offset:49348
	ds_write_b32 v33, v74 offset:49352
	ds_write_b32 v33, v75 offset:49356
	ds_write_b32 v33, v76 offset:57568
	ds_write_b32 v33, v77 offset:57572
	ds_write_b32 v33, v78 offset:57576
	ds_write_b32 v33, v79 offset:57580
	s_waitcnt lgkmcnt(0)
	s_barrier
	s_add_u32 s10, s6, s20
	s_addc_u32 s11, s7, 0
	ds_read_b32 v36, v34 offset:0
	ds_read_b32 v37, v34 offset:1028
	ds_read_b32 v38, v34 offset:2056
	ds_read_b32 v39, v34 offset:3084
	ds_read_b32 v40, v34 offset:4112
	ds_read_b32 v41, v34 offset:5140
	ds_read_b32 v42, v34 offset:6168
	ds_read_b32 v43, v34 offset:7196
	s_waitcnt lgkmcnt(0)
	v_cvt_pk_bf16_f32 v44, v36, v37
	v_cvt_pk_bf16_f32 v45, v38, v39
	v_cvt_pk_bf16_f32 v46, v40, v41
	v_cvt_pk_bf16_f32 v47, v42, v43
	global_store_dwordx4 v35, v[44:47], s[10:11]
	s_add_u32 s10, s10, 0xb0000
	s_addc_u32 s11, s11, 0
	ds_read_b32 v36, v34 offset:256
	ds_read_b32 v37, v34 offset:1284
	ds_read_b32 v38, v34 offset:2312
	ds_read_b32 v39, v34 offset:3340
	ds_read_b32 v40, v34 offset:4368
	ds_read_b32 v41, v34 offset:5396
	ds_read_b32 v42, v34 offset:6424
	ds_read_b32 v43, v34 offset:7452
	s_waitcnt lgkmcnt(0)
	v_cvt_pk_bf16_f32 v44, v36, v37
	v_cvt_pk_bf16_f32 v45, v38, v39
	v_cvt_pk_bf16_f32 v46, v40, v41
	v_cvt_pk_bf16_f32 v47, v42, v43
	global_store_dwordx4 v35, v[44:47], s[10:11]
	s_add_u32 s10, s10, 0xb0000
	s_addc_u32 s11, s11, 0
	ds_read_b32 v36, v34 offset:512
	ds_read_b32 v37, v34 offset:1540
	ds_read_b32 v38, v34 offset:2568
	ds_read_b32 v39, v34 offset:3596
	ds_read_b32 v40, v34 offset:4624
	ds_read_b32 v41, v34 offset:5652
	ds_read_b32 v42, v34 offset:6680
	ds_read_b32 v43, v34 offset:7708
	s_waitcnt lgkmcnt(0)
	v_cvt_pk_bf16_f32 v44, v36, v37
	v_cvt_pk_bf16_f32 v45, v38, v39
	v_cvt_pk_bf16_f32 v46, v40, v41
	v_cvt_pk_bf16_f32 v47, v42, v43
	global_store_dwordx4 v35, v[44:47], s[10:11]
	s_add_u32 s10, s10, 0xb0000
	s_addc_u32 s11, s11, 0
	ds_read_b32 v36, v34 offset:768
	ds_read_b32 v37, v34 offset:1796
	ds_read_b32 v38, v34 offset:2824
	ds_read_b32 v39, v34 offset:3852
	ds_read_b32 v40, v34 offset:4880
	ds_read_b32 v41, v34 offset:5908
	ds_read_b32 v42, v34 offset:6936
	ds_read_b32 v43, v34 offset:7964
	s_waitcnt lgkmcnt(0)
	v_cvt_pk_bf16_f32 v44, v36, v37
	v_cvt_pk_bf16_f32 v45, v38, v39
	v_cvt_pk_bf16_f32 v46, v40, v41
	v_cvt_pk_bf16_f32 v47, v42, v43
	global_store_dwordx4 v35, v[44:47], s[10:11]
	s_barrier
	s_add_i32 s12, s12, 40
	s_cmpk_lt_i32 s12, 704
	s_cbranch_scc0 .Lmy_cv9_end
	s_mov_b32 s20, s21
	s_mov_b32 s21, s23
.Lmy_cv9_b2:
	s_add_i32 s13, s12, 80
	s_cmpk_lt_i32 s13, 704
	s_cbranch_scc0 .Lmy_cv9_b2_no2
	s_lshr_b32 s16, s13, 3
	s_and_b32 s17, s13, 7
	s_lshl_b32 s18, s16, 19
	s_lshl_b32 s19, s80, 13
	s_add_i32 s18, s18, s19
	s_lshl_b32 s19, s17, 10
	s_add_i32 s18, s18, s19
	s_add_u32 s8, s4, s18
	s_addc_u32 s9, s5, 0
	s_mul_i32 s18, s17, 0x2c0000
	s_lshl_b32 s19, s16, 7
	s_add_i32 s18, s18, s19
	s_mov_b32 s23, s18
	global_load_dwordx4 v[48:51], v32, s[8:9] nt
	s_add_u32 s8, s8, 0x10000
	s_addc_u32 s9, s9, 0
	global_load_dwordx4 v[52:55], v32, s[8:9] nt
	s_add_u32 s8, s8, 0x10000
	s_addc_u32 s9, s9, 0
	global_load_dwordx4 v[56:59], v32, s[8:9] nt
	s_add_u32 s8, s8, 0x10000
	s_addc_u32 s9, s9, 0
	global_load_dwordx4 v[60:63], v32, s[8:9] nt
	s_add_u32 s8, s8, 0x10000
	s_addc_u32 s9, s9, 0
	global_load_dwordx4 v[64:67], v32, s[8:9] nt
	s_add_u32 s8, s8, 0x10000
	s_addc_u32 s9, s9, 0
	global_load_dwordx4 v[68:71], v32, s[8:9] nt
	s_add_u32 s8, s8, 0x10000
	s_addc_u32 s9, s9, 0
	global_load_dwordx4 v[72:75], v32, s[8:9] nt
	s_add_u32 s8, s8, 0x10000
	s_addc_u32 s9, s9, 0
	global_load_dwordx4 v[76:79], v32, s[8:9] nt
	s_waitcnt vmcnt(16)
	s_branch .Lmy_cv9_b2_go

; #define LAS __attribute__((address_space(3)))
; __device__ __forceinline__ void convert_tiles(const Frame& F, int tlo, int thi, int wb, int nw) {
;     ...
;     for (;;) {
; #pragma unroll
;         for (int i = 0; i < 8; ++i) { LAS float* tp = tile + (i * 8 + F.wave) * 257 + F.lane * 4; tp[0] = v[i][0]; tp[1] = v[i][1]; tp[2] = v[i][2]; tp[3] = v[i][3]; }
;         __syncthreads();
;         const int tn = t + nw; const bool more = tn < thi; TileDesc dn = d;
;         if (more) { dn = tile_desc(F, tn);
; #pragma unroll
;             for (int i = 0; i < 8; ++i) v[i] = __builtin_nontemporal_load((const f32x4*)(dn.src + (size_t)(dn.k0 + i * 8 + F.wave) * dn.ldn + dn.n0 + F.lane * 4)); }
; #pragma unroll
;         for (int it = 0; it < 4; ++it) { const int item = it * 512 + F.tid, n = item >> 3, kg = item & 7;
;             float f[8];
; #pragma unroll
;             for (int j = 0; j < 8; ++j) f[j] = tile[(kg * 8 + j) * 257 + n];
;             const int nn = d.n0 + n; const int row = d.kind == 0 ? nn : (((nn >> 7) << 8) + (nn & 127) + (d.kind == 2 ? 128 : 0));
;             *(u32x4*)(d.dst + (size_t)row * d.K + d.k0 + kg * 8) = pack8(f); }
;         __syncthreads();
;         if (!more) break;
;         t = tn; d = dn;
;     }
.Lmy_cv9_b2_go:
	ds_write_b32 v33, v80 offset:0
	ds_write_b32 v33, v81 offset:4
	ds_write_b32 v33, v82 offset:8
	ds_write_b32 v33, v83 offset:12
	ds_write_b32 v33, v84 offset:8224
	ds_write_b32 v33, v85 offset:8228
	ds_write_b32 v33, v86 offset:8232
	ds_write_b32 v33, v87 offset:8236
	ds_write_b32 v33, v88 offset:16448
	ds_write_b32 v33, v89 offset:16452
	ds_write_b32 v33, v90 offset:16456
	ds_write_b32 v33, v91 offset:16460
	ds_write_b32 v33, v92 offset:24672
	ds_write_b32 v33, v93 offset:24676
	ds_write_b32 v33, v94 offset:24680
	ds_write_b32 v33, v95 offset:24684
	ds_write_b32 v33, v96 offset:32896
	ds_write_b32 v33, v97 offset:32900
	ds_write_b32 v33, v98 offset:32904
	ds_write_b32 v33, v99 offset:32908
	ds_write_b32 v33, v100 offset:41120
	ds_write_b32 v33, v101 offset:41124
	ds_write_b32 v33, v102 offset:41128
	ds_write_b32 v33, v103 offset:41132
	ds_write_b32 v33, v104 offset:49344
	ds_write_b32 v33, v105 offset:49348
	ds_write_b32 v33, v106 offset:49352
	ds_write_b32 v33, v107 offset:49356
	ds_write_b32 v33, v108 offset:57568
	ds_write_b32 v33, v109 offset:57572
	ds_write_b32 v33, v110 offset:57576
	ds_write_b32 v33, v111 offset:57580
	s_waitcnt lgkmcnt(0)
	s_barrier
	s_add_u32 s10, s6, s20
	s_addc_u32 s11, s7, 0
	ds_read_b32 v36, v34 offset:0
	ds_read_b32 v37, v34 offset:1028
	ds_read_b32 v38, v34 offset:2056
	ds_read_b32 v39, v34 offset:3084
	ds_read_b32 v40, v34 offset:4112
	ds_read_b32 v41, v34 offset:5140
	ds_read_b32 v42, v34 offset:6168
	ds_read_b32 v43, v34 offset:7196
	s_waitcnt lgkmcnt(0)
	v_cvt_pk_bf16_f32 v44, v36, v37
	v_cvt_pk_bf16_f32 v45, v38, v39
	v_cvt_pk_bf16_f32 v46, v40, v41
	v_cvt_pk_bf16_f32 v47, v42, v43
	global_store_dwordx4 v35, v[44:47], s[10:11]
	s_add_u32 s10, s10, 0xb0000
	s_addc_u32 s11, s11, 0
	ds_read_b32 v36, v34 offset:256
	ds_read_b32 v37, v34 offset:1284
	ds_read_b32 v38, v34 offset:2312
	ds_read_b32 v39, v34 offset:3340
	ds_read_b32 v40, v34 offset:4368
	ds_read_b32 v41, v34 offset:5396
	ds_read_b32 v42, v34 offset:6424
	ds_read_b32 v43, v34 offset:7452
	s_waitcnt lgkmcnt(0)
	v_cvt_pk_bf16_f32 v44, v36, v37
	v_cvt_pk_bf16_f32 v45, v38, v39
	v_cvt_pk_bf16_f32 v46, v40, v41
	v_cvt_pk_bf16_f32 v47, v42, v43
	global_store_dwordx4 v35, v[44:47], s[10:11]
	s_add_u32 s10, s10, 0xb0000
	s_addc_u32 s11, s11, 0
	ds_read_b32 v36, v34 offset:512
	ds_read_b32 v37, v34 offset:1540
	ds_read_b32 v38, v34 offset:2568
	ds_read_b32 v39, v34 offset:3596
	ds_read_b32 v40, v34 offset:4624
	ds_read_b32 v41, v34 offset:5652
	ds_read_b32 v42, v34 offset:6680
	ds_read_b32 v43, v34 offset:7708
	s_waitcnt lgkmcnt(0)
	v_cvt_pk_bf16_f32 v44, v36, v37
	v_cvt_pk_bf16_f32 v45, v38, v39
	v_cvt_pk_bf16_f32 v46, v40, v41
	v_cvt_pk_bf16_f32 v47, v42, v43
	global_store_dwordx4 v35, v[44:47], s[10:11]
	s_add_u32 s10, s10, 0xb0000
	s_addc_u32 s11, s11, 0
	ds_read_b32 v36, v34 offset:768
	ds_read_b32 v37, v34 offset:1796
	ds_read_b32 v38, v34 offset:2824
	ds_read_b32 v39, v34 offset:3852
	ds_read_b32 v40, v34 offset:4880
	ds_read_b32 v41, v34 offset:5908
	ds_read_b32 v42, v34 offset:6936
	ds_read_b32 v43, v34 offset:7964
	s_waitcnt lgkmcnt(0)
	v_cvt_pk_bf16_f32 v44, v36, v37
	v_cvt_pk_bf16_f32 v45, v38, v39
	v_cvt_pk_bf16_f32 v46, v40, v41
	v_cvt_pk_bf16_f32 v47, v42, v43
	global_store_dwordx4 v35, v[44:47], s[10:11]
	s_barrier
	s_add_i32 s12, s12, 40
	s_cmpk_lt_i32 s12, 704
	s_cbranch_scc0 .Lmy_cv9_end
	s_mov_b32 s20, s21
	s_mov_b32 s21, s23
	s_branch .Lmy_cv9_loop
